# v109 + next-tile ticket prefetch in E1 only (atomic issued at K-loop exit, consumed at the tile-loop head; E1 no longer ends at a barrier)
# baseline (speedup 1.0000x reference)
; #define LAS __attribute__((address_space(3)))
; __device__ __forceinline__ unsigned xb_add(unsigned* p, unsigned v) { return __hip_atomic_fetch_add(p, v, __ATOMIC_RELAXED, __HIP_MEMORY_SCOPE_AGENT); }
; __device__ __forceinline__ unsigned xb_xcc_id() { return (unsigned)__builtin_amdgcn_s_getreg((3 << 11) | 20) & 0xFu; }
; __device__ __forceinline__ XcdBarrier xcd_barrier_post(unsigned* bar, volatile LAS unsigned* st) {
;   XcdBarrier b; b.bar = bar; b.x = xb_xcc_id(); b.st = st;
;   if (threadIdx.x == 0) (void)xb_add(&bar[XB_XCNT(b.x)], 1u);
;   return b;
; __global__ void __launch_bounds__(256, 2) fwd_megakernel(Params p) {
;   extern __shared__ __attribute__((aligned(16))) char smem[];
;   cg::grid_group grid = cg::this_grid();
;   volatile LAS unsigned* st = (volatile LAS unsigned*)(smem + AUX_OFF + 768);
;   if (threadIdx.x < 2) st[threadIdx.x] = 0u;
;   __syncthreads();
;   XcdBarrier xb = xcd_barrier_post(p.bar, st);
_Z14fwd_megakernel6Params:
	v_mov_b32_e32 v241, -1
	s_load_dword s3, s[0:1], 0x150
	s_load_dwordx2 s[4:5], s[0:1], 0x148
	s_load_dwordx16 s[68:83], s[0:1], 0x100
	s_add_u32 s6, s0, 0x148
	s_addc_u32 s7, s1, 0
	s_waitcnt lgkmcnt(0)
	v_writelane_b32 v240, s3, 0
	v_writelane_b32 v240, s4, 1
	v_and_b32_e32 v128, 0x3ff, v0
	v_cmp_gt_u32_e32 vcc, 2, v128
	v_writelane_b32 v240, s5, 2
	v_writelane_b32 v240, s6, 3
	v_lshl_add_u32 v131, v128, 2, 0
	s_nop 0
	v_writelane_b32 v240, s7, 4
	s_and_saveexec_b64 s[6:7], vcc
	v_add_u32_e32 v1, 0x10300, v131
	v_mov_b32_e32 v2, 0
	ds_write_b32 v1, v2
	s_or_b64 exec, exec, s[6:7]
	s_load_dword s6, s[0:1], 0x140
	s_waitcnt lgkmcnt(0)
	s_barrier
	s_getreg_b32 s3, hwreg(HW_REG_XCC_ID, 0, 4)
	s_and_b32 s3, s3, 15
	v_cmp_eq_u32_e64 s[34:35], 0, v128
	v_writelane_b32 v240, s3, 5
	s_and_saveexec_b64 s[10:11], s[34:35]
	s_cbranch_execz .LBB0_5
	s_mov_b64 s[4:5], exec
	v_mbcnt_lo_u32_b32 v1, s4, 0
	v_mbcnt_hi_u32_b32 v1, s5, v1
	v_cmp_eq_u32_e32 vcc, 0, v1
	s_and_b64 s[8:9], exec, vcc
	s_mov_b64 exec, s[8:9]
	s_cbranch_execz .LBB0_5
	v_readlane_b32 s3, v240, 5
	s_lshl_b32 s7, s3, 8
	s_bcnt1_i32_b64 s4, s[4:5]
	v_mov_b32_e32 v1, s7
	v_mov_b32_e32 v2, s4
	global_atomic_add v1, v2, s[82:83] offset:1024

; template <class F>
; __device__ __forceinline__ void xcd_queue_run(unsigned* qwords, int nper, char* smem_aux, F fn) {
;     ...
;     for (;;) {
;       __syncthreads();
;       if (threadIdx.x == 0) *slot = (int)__hip_atomic_fetch_add(qwords + 64 * j, 1u, __ATOMIC_RELAXED, __HIP_MEMORY_SCOPE_AGENT);
;       __syncthreads();
.Le1_nosig:
	s_mov_b32 s51, s32
	s_mov_b32 s32, -1
	s_mov_b64 s[20:21], exec
	v_mbcnt_lo_u32_b32 v0, s20, 0
	v_mbcnt_hi_u32_b32 v0, s21, v0
	v_cmp_eq_u32_e32 vcc, 0, v0
	s_and_saveexec_b64 s[18:19], vcc
	s_cbranch_execz .LBB0_1272
	s_waitcnt vmcnt(0)
	v_cmp_ne_u32_e32 vcc, -1, v241
	s_cbranch_vccz .Ltp_E1_do
	v_mov_b32_e32 v1, v241
	v_mov_b32_e32 v241, -1
	s_branch .LBB0_1272

; __device__ __forceinline__ float siluf(float x) { return x / (1.f + __expf(-x)); }
; template <class F>
; __device__ __forceinline__ void xcd_queue_run(unsigned* qwords, int nper, char* smem_aux, F fn) {
;     ...
;       __syncthreads();
;       if (threadIdx.x == 0) *slot = (int)__hip_atomic_fetch_add(qwords + 64 * j, 1u, __ATOMIC_RELAXED, __HIP_MEMORY_SCOPE_AGENT);
;       __syncthreads();
; __device__ void phaseE1(const Params& p, char* smem) {
;     ...
;     auto epi = [&](f32x4 (&acc)[4][4], int mb, int nb) {
;       const int wn = nb >> 6, kg4 = nb & 63;
; #pragma unroll
;       for (int mi = 0; mi < 4; mi++) {
;         const int r = mb + mi * 16;
;         if (r < rows) {
; #pragma unroll
;           for (int ni = 0; ni < 2; ni++) {
;             f32x4 gv = acc[mi][ni], uv = acc[mi][ni + 2];
;             uint2 o;
;             o.x = pack2(siluf(gv[0]) * uv[0], siluf(gv[1]) * uv[1]);
;             o.y = pack2(siluf(gv[2]) * uv[2], siluf(gv[3]) * uv[3]);
;             *(uint2*)&p.H[(size_t)(slot0 + r) * DEXP + j0 + wn * 32 + ni * 16 + kg4] = o;
;           }
;         }
;       }
;     };
.LBB0_1282:
	s_mov_b64 s[100:101], exec
	s_and_b64 exec, exec, s[34:35]
	s_cbranch_execz .Ltp_E1_np
	v_mov_b32_e32 v242, 0
	v_mov_b32_e32 v241, 1
	global_atomic_add v241, v242, v241, s[12:13] sc0
.Ltp_E1_np:
	s_mov_b64 exec, s[100:101]
	s_waitcnt vmcnt(3)
	v_add_u32_e32 v64, v96, v122
	v_cmp_lt_i32_e32 vcc, v126, v123
	s_and_saveexec_b64 s[18:19], vcc
	s_cbranch_execnz .LBB0_1288
	s_or_b64 exec, exec, s[18:19]
	v_cmp_lt_i32_e32 vcc, v166, v123
	s_and_saveexec_b64 s[18:19], vcc
	s_cbranch_execnz .LBB0_1289
